# attncsel + grid barrier: non-last XCD leaders issue their L1 invalidate before spinning on the cross-XCD release
# baseline (speedup 1.0000x reference)
; __device__ __forceinline__ unsigned xb_ld(unsigned* p)              { return __hip_atomic_load(p, __ATOMIC_RELAXED, __HIP_MEMORY_SCOPE_AGENT); }
; __device__ __forceinline__ unsigned xb_add(unsigned* p, unsigned v) { return __hip_atomic_fetch_add(p, v, __ATOMIC_RELAXED, __HIP_MEMORY_SCOPE_AGENT); }
; #define XB_SPIN(cond, bar) do { unsigned _sp = 0; while (cond) { __builtin_amdgcn_s_sleep(1); \
;     if ((++_sp & 255u) == 0u) { if (xb_ld(&(bar)[XB_TMO])) break; if (_sp > XB_SPIN_CAP) { atomicAdd(&(bar)[XB_TMO], 1u); break; } } } } while (0)
; __device__ __forceinline__ void xcd_barrier(const XcdBarrier& b) {
;     asm volatile("s_waitcnt vmcnt(0)" ::: "memory");
;     __syncthreads();
;     if (threadIdx.x == 0) {
;         unsigned* bar = b.bar;
;         __builtin_amdgcn_s_waitcnt(0);
;         unsigned nloc = b.st[0], nx = b.st[1];
;         if (nloc == 0u) { xcd_barrier_complete(bar, b.x, nloc, nx); b.st[0] = nloc; b.st[1] = nx; }
;         const unsigned old = xb_add(&bar[XB_XSUB(b.x)], 1u);
;         const unsigned gen = old / nloc;
;         if (old + 1u == (gen + 1u) * nloc) {
;             __builtin_amdgcn_fence(__ATOMIC_RELEASE, "agent");
;             asm volatile("s_waitcnt vmcnt(0)" ::: "memory");
;             const unsigned og = xb_add(&bar[XB_TOP], 1u);
;             const unsigned tg = og / nx;
;             if (og + 1u == (tg + 1u) * nx) xb_add(&bar[XB_TOPGEN], 1u);
;             else XB_SPIN(xb_ld(&bar[XB_TOPGEN]) == tg, bar);
;             __builtin_amdgcn_fence(__ATOMIC_ACQUIRE, "agent");
;             xb_add(&bar[XB_XGEN(b.x)], 1u);
;             asm volatile("s_waitcnt vmcnt(0)" ::: "memory");
;         } else {
;             XB_SPIN(xb_ld(&bar[XB_XGEN(b.x)]) == gen, bar);
;             __builtin_amdgcn_fence(__ATOMIC_ACQUIRE, "agent");
;             asm volatile("s_waitcnt vmcnt(0)" ::: "memory");
;         }
.LBB0_617:
	s_andn2_saveexec_b64 s[18:19], s[18:19]
	s_cbranch_execz .LBB0_637
	s_mov_b32 s69, 0
	s_mov_b64 s[18:19], exec
	buffer_wbl2 sc1
	s_waitcnt lgkmcnt(0)
	s_waitcnt vmcnt(0)
	v_mbcnt_lo_u32_b32 v1, s18, 0
	v_mbcnt_hi_u32_b32 v1, s19, v1
	v_cmp_eq_u32_e32 vcc, 0, v1
	s_and_saveexec_b64 s[20:21], vcc
	s_cbranch_execz .LBB0_620
	s_bcnt1_i32_b64 s2, s[18:19]
	v_readlane_b32 s4, v253, 54
	v_mov_b32_e32 v2, s2
	v_readlane_b32 s5, v253, 55
	s_nop 4
	global_atomic_add v2, v144, v2, s[4:5] sc0
.LBB0_620:
	s_or_b64 exec, exec, s[20:21]
	s_waitcnt vmcnt(0)
	v_readfirstlane_b32 s2, v2
	v_cvt_f32_u32_e32 v2, v0
	v_sub_u32_e32 v3, 0, v0
	v_add_u32_e32 v1, s2, v1
	v_readlane_b32 s4, v253, 56
	v_rcp_iflag_f32_e32 v2, v2
	v_readlane_b32 s5, v253, 57
	s_mov_b64 s[20:21], -1
	v_mul_f32_e32 v2, 0x4f7ffffe, v2
	v_cvt_u32_f32_e32 v2, v2
	v_mul_lo_u32 v3, v3, v2
	v_mul_hi_u32 v3, v2, v3
	v_add_u32_e32 v2, v2, v3
	v_mul_hi_u32 v2, v1, v2
	v_mul_lo_u32 v3, v2, v0
	v_sub_u32_e32 v3, v1, v3
	v_cmp_ge_u32_e32 vcc, v3, v0
	v_add_u32_e32 v4, 1, v2
	v_add_u32_e32 v1, 1, v1
	v_cndmask_b32_e32 v2, v2, v4, vcc
	v_sub_u32_e32 v4, v3, v0
	v_cndmask_b32_e32 v3, v3, v4, vcc
	v_cmp_ge_u32_e32 vcc, v3, v0
	v_add_u32_e32 v3, 1, v2
	s_nop 0
	v_cndmask_b32_e32 v2, v2, v3, vcc
	v_mul_lo_u32 v3, v0, v2
	v_add_u32_e32 v0, v3, v0
	v_cmp_ne_u32_e32 vcc, v1, v0
	v_mov_b64_e32 v[0:1], s[4:5]
	s_and_saveexec_b64 s[18:19], vcc
	s_cbranch_execz .LBB0_632
	s_mov_b32 s69, 1
	buffer_inv sc1
	v_readlane_b32 s4, v253, 56
	v_readlane_b32 s5, v253, 57
	s_mov_b64 s[26:27], 0
	s_nop 3
	global_load_dword v0, v144, s[4:5] sc1
	s_waitcnt vmcnt(0)
	v_cmp_eq_u32_e32 vcc, v0, v2
	s_and_saveexec_b64 s[20:21], vcc
	s_cbranch_execz .LBB0_631
	s_mov_b32 s2, 1
	s_mov_b64 s[28:29], 0
	s_branch .LBB0_624

; __device__ __forceinline__ unsigned xb_ld(unsigned* p)              { return __hip_atomic_load(p, __ATOMIC_RELAXED, __HIP_MEMORY_SCOPE_AGENT); }
; __device__ __forceinline__ unsigned xb_add(unsigned* p, unsigned v) { return __hip_atomic_fetch_add(p, v, __ATOMIC_RELAXED, __HIP_MEMORY_SCOPE_AGENT); }
; #define XB_SPIN(cond, bar) do { unsigned _sp = 0; while (cond) { __builtin_amdgcn_s_sleep(1); \
;     if ((++_sp & 255u) == 0u) { if (xb_ld(&(bar)[XB_TMO])) break; if (_sp > XB_SPIN_CAP) { atomicAdd(&(bar)[XB_TMO], 1u); break; } } } } while (0)
; __device__ __forceinline__ void xcd_barrier(const XcdBarrier& b) {
;     ...
;             __builtin_amdgcn_fence(__ATOMIC_ACQUIRE, "agent");
;             xb_add(&bar[XB_XGEN(b.x)], 1u);
;             asm volatile("s_waitcnt vmcnt(0)" ::: "memory");
;         } else {
;             XB_SPIN(xb_ld(&bar[XB_XGEN(b.x)]) == gen, bar);
;             __builtin_amdgcn_fence(__ATOMIC_ACQUIRE, "agent");
;             asm volatile("s_waitcnt vmcnt(0)" ::: "memory");
;         }
.LBB0_634:
	s_or_b64 exec, exec, s[18:19]
	s_mov_b64 s[18:19], exec
	v_mbcnt_lo_u32_b32 v0, s18, 0
	v_mbcnt_hi_u32_b32 v0, s19, v0
	v_cmp_eq_u32_e32 vcc, 0, v0
	s_waitcnt vmcnt(0)
	s_cmp_eq_u32 s69, 1
	s_cbranch_scc1 .Lskipinv_ldr
	buffer_inv sc1
.Lskipinv_ldr:
	s_and_saveexec_b64 s[20:21], vcc
	s_cbranch_execz .LBB0_636
	s_bcnt1_i32_b64 s2, s[18:19]
	v_readlane_b32 s4, v253, 52
	v_mov_b32_e32 v0, s2
	v_readlane_b32 s5, v253, 53
	s_nop 4
	global_atomic_add v144, v0, s[4:5]
